# G1 start skew s_sleep 40 per group (v75 otherwise)
# speedup vs baseline: 1.0046x; 1.0046x over previous
.Lskew_loop_g1:
	s_sleep 40
	s_sub_u32 s4, s4, 1
	s_cmp_lg_u32 s4, 0
	s_cbranch_scc1 .Lskew_loop_g1
